# scan: one workgroup barrier per four chunks instead of two (loaders issue four chunks per period, six chunks in flight)
# baseline (speedup 1.0000x reference)
; #define SP_BAR() asm volatile("s_waitcnt lgkmcnt(0)\n\ts_barrier" ::: "memory")
; #define SP_WAIT() asm volatile("s_waitcnt vmcnt(36)" ::: "memory")
; __device__ __forceinline__ void p3_rwkv_state(Frame& F, const Args& a) {
;     ...
;     if (loader) {
;         DmaPtrs P; rw_dma_init(a, P, head, ib, lw, lane);
;         for (int n = 0; n < SP_D; ++n) rw_dma_issue(P, lw, lane, lds0 + (unsigned)(n % SP_R) * SP_SLOT);
;         SP_WAIT();
;         SP_BAR();
;         for (int n = 0; n < NC; n += 2) {
;             if (n + SP_D + 1 < NC) { rw_dma_issue(P, lw, lane, lds0 + (unsigned)((n + SP_D) % SP_R) * SP_SLOT); rw_dma_issue(P, lw, lane, lds0 + (unsigned)((n + SP_D + 1) % SP_R) * SP_SLOT); SP_WAIT(); }
;             else asm volatile("s_waitcnt vmcnt(0)" ::: "memory");
;             SP_BAR();
;         }
.Lscan_ldbig_pro:
	s_add_i32 s16, s15, s14
	s_mov_b32 m0, s16
	s_add_i32 s15, s15, 0x2800
	global_load_lds_dwordx4 v[2:3], off
	global_load_lds_dwordx4 v[2:3], off offset:1024
	s_cmp_eq_u32 s15, 0x25800
	s_cselect_b32 s15, 0, s15
	v_lshl_add_u64 v[2:3], v[2:3], 0, s[6:7]
	s_add_i32 s18, s18, 1
	s_cmp_lt_u32 s18, 11
	s_cbranch_scc1 .Lscan_ldbig_pro
	s_waitcnt vmcnt(12)
	s_barrier
	s_mov_b32 s18, 0
	s_movk_i32 s17, 0x100
.Lscan_ldbig_loop:
	s_cmpk_gt_u32 s18, 0x3f4
	s_cbranch_scc1 .Lscan_ldbig_tail
.Lscan_ldbig_chk:
	s_add_i32 s24, s18, 14
	s_min_u32 s24, s24, 0x3ff
	s_lshr_b32 s24, s24, 1
	s_cmp_lt_u32 s24, s17
	s_cbranch_scc1 .Lscan_ldbig_go
	v_add_u32_e32 v12, s17, v76
	v_lshlrev_b32_e32 v13, 2, v12
	v_add_u32_e32 v13, 0x8000, v13
	global_load_dword v13, v13, s[90:91] sc1
	s_movk_i32 s24, 0x1ff
	s_waitcnt vmcnt(0)
	v_cmp_ne_u32_e64 s[20:21], 0, v13
	v_cmp_lt_u32_e64 s[22:23], s24, v12
	s_nop 1
	s_or_b64 s[20:21], s[20:21], s[22:23]
	s_not_b64 s[20:21], s[20:21]
	s_ff1_i32_b64 s24, s[20:21]
	s_cmp_eq_u32 s24, -1
	s_cselect_b32 s24, 64, s24
	s_add_i32 s17, s17, s24
	s_cmp_lg_u32 s24, 0
	s_cbranch_scc1 .Lscan_ldbig_chk
	s_sleep 8
	s_branch .Lscan_ldbig_chk
.Lscan_ldbig_go:
	s_add_i32 s16, s15, s14
	s_mov_b32 m0, s16
	s_add_i32 s15, s15, 0x2800
	global_load_lds_dwordx4 v[2:3], off
	global_load_lds_dwordx4 v[2:3], off offset:1024
	s_cmp_eq_u32 s15, 0x25800
	s_cselect_b32 s15, 0, s15
	v_lshl_add_u64 v[2:3], v[2:3], 0, s[6:7]
	s_add_i32 s25, s18, 12
	s_cmpk_gt_u32 s25, 0x3ff
	s_cbranch_scc1 .Lscan_ldbig_w
	s_add_i32 s16, s15, s14
	s_mov_b32 m0, s16
	s_add_i32 s15, s15, 0x2800
	global_load_lds_dwordx4 v[2:3], off
	global_load_lds_dwordx4 v[2:3], off offset:1024
	s_cmp_eq_u32 s15, 0x25800
	s_cselect_b32 s15, 0, s15
	v_lshl_add_u64 v[2:3], v[2:3], 0, s[6:7]
	s_add_i32 s25, s18, 13
	s_cmpk_gt_u32 s25, 0x3ff
	s_cbranch_scc1 .Lscan_ldbig_w
	s_add_i32 s16, s15, s14
	s_mov_b32 m0, s16
	s_add_i32 s15, s15, 0x2800
	global_load_lds_dwordx4 v[2:3], off
	global_load_lds_dwordx4 v[2:3], off offset:1024
	s_cmp_eq_u32 s15, 0x25800
	s_cselect_b32 s15, 0, s15
	v_lshl_add_u64 v[2:3], v[2:3], 0, s[6:7]
	s_add_i32 s25, s18, 14
	s_cmpk_gt_u32 s25, 0x3ff
	s_cbranch_scc1 .Lscan_ldbig_w
	s_add_i32 s16, s15, s14
	s_mov_b32 m0, s16
	s_add_i32 s15, s15, 0x2800
	global_load_lds_dwordx4 v[2:3], off
	global_load_lds_dwordx4 v[2:3], off offset:1024
	s_cmp_eq_u32 s15, 0x25800
	s_cselect_b32 s15, 0, s15
	v_lshl_add_u64 v[2:3], v[2:3], 0, s[6:7]
	s_waitcnt vmcnt(12)
	s_branch .Lscan_ldbig_bar
.Lscan_ldbig_w:
.Lscan_ldbig_tail:
	s_waitcnt vmcnt(0)
.Lscan_ldbig_bar:
	s_barrier
	s_add_i32 s18, s18, 4
	s_cmpk_lt_u32 s18, 0x400
	s_cbranch_scc1 .Lscan_ldbig_loop
	s_mov_b32 m0, s19
	s_branch .LBB0_456

; #define SP_BAR() asm volatile("s_waitcnt lgkmcnt(0)\n\ts_barrier" ::: "memory")
; #define SP_WAIT() asm volatile("s_waitcnt vmcnt(36)" ::: "memory")
; __device__ __forceinline__ void p3_rwkv_state(Frame& F, const Args& a) {
;     ...
;     if (loader) {
;         DmaPtrs P; rw_dma_init(a, P, head, ib, lw, lane);
;         for (int n = 0; n < SP_D; ++n) rw_dma_issue(P, lw, lane, lds0 + (unsigned)(n % SP_R) * SP_SLOT);
;         SP_WAIT();
;         SP_BAR();
.Lscan_ldsmall_pro:
	s_add_i32 s16, s15, 0x2000
	s_mov_b32 m0, s16
	s_mov_b32 exec_hi, 0
	s_add_i32 s15, s15, 0x2800
	global_load_lds_dwordx4 v[2:3], off
	global_load_lds_dwordx4 v[4:5], off offset:512
	global_load_lds_dwordx4 v[6:7], off offset:1024
	s_mov_b32 exec_lo, 0xffff
	s_cmp_eq_u32 s15, 0x25800
	global_load_lds_dwordx4 v[8:9], off offset:1536
	s_mov_b64 exec, -1
	s_cselect_b32 s15, 0, s15
	v_lshl_add_u64 v[2:3], v[2:3], 0, s[6:7]
	v_lshl_add_u64 v[4:5], v[4:5], 0, s[6:7]
	v_lshl_add_u64 v[6:7], v[6:7], 0, s[6:7]
	v_lshl_add_u64 v[8:9], v[8:9], 0, s[10:11]
	s_add_i32 s18, s18, 1
	s_cmp_lt_u32 s18, 11
	s_cbranch_scc1 .Lscan_ldsmall_pro
	s_waitcnt vmcnt(24)
	s_barrier
	s_mov_b32 s18, 0
	s_movk_i32 s17, 0x100

; #define SP_BAR() asm volatile("s_waitcnt lgkmcnt(0)\n\ts_barrier" ::: "memory")
; #define SP_WAIT() asm volatile("s_waitcnt vmcnt(36)" ::: "memory")
; __device__ __forceinline__ void p3_rwkv_state(Frame& F, const Args& a) {
;     ...
;         for (int n = 0; n < NC; n += 2) {
;             if (n + SP_D + 1 < NC) { rw_dma_issue(P, lw, lane, lds0 + (unsigned)((n + SP_D) % SP_R) * SP_SLOT); rw_dma_issue(P, lw, lane, lds0 + (unsigned)((n + SP_D + 1) % SP_R) * SP_SLOT); SP_WAIT(); }
;             else asm volatile("s_waitcnt vmcnt(0)" ::: "memory");
;             SP_BAR();
;         }
.Lscan_ldsmall_go:
	s_add_i32 s16, s15, 0x2000
	s_mov_b32 m0, s16
	s_mov_b32 exec_hi, 0
	s_add_i32 s15, s15, 0x2800
	global_load_lds_dwordx4 v[2:3], off
	global_load_lds_dwordx4 v[4:5], off offset:512
	global_load_lds_dwordx4 v[6:7], off offset:1024
	s_mov_b32 exec_lo, 0xffff
	s_cmp_eq_u32 s15, 0x25800
	global_load_lds_dwordx4 v[8:9], off offset:1536
	s_mov_b64 exec, -1
	s_cselect_b32 s15, 0, s15
	v_lshl_add_u64 v[2:3], v[2:3], 0, s[6:7]
	v_lshl_add_u64 v[4:5], v[4:5], 0, s[6:7]
	v_lshl_add_u64 v[6:7], v[6:7], 0, s[6:7]
	v_lshl_add_u64 v[8:9], v[8:9], 0, s[10:11]
	s_add_i32 s25, s18, 12
	s_cmpk_gt_u32 s25, 0x3ff
	s_cbranch_scc1 .Lscan_ldsmall_w
	s_add_i32 s16, s15, 0x2000
	s_mov_b32 m0, s16
	s_mov_b32 exec_hi, 0
	s_add_i32 s15, s15, 0x2800
	global_load_lds_dwordx4 v[2:3], off
	global_load_lds_dwordx4 v[4:5], off offset:512
	global_load_lds_dwordx4 v[6:7], off offset:1024
	s_mov_b32 exec_lo, 0xffff
	s_cmp_eq_u32 s15, 0x25800
	global_load_lds_dwordx4 v[8:9], off offset:1536
	s_mov_b64 exec, -1
	s_cselect_b32 s15, 0, s15
	v_lshl_add_u64 v[2:3], v[2:3], 0, s[6:7]
	v_lshl_add_u64 v[4:5], v[4:5], 0, s[6:7]
	v_lshl_add_u64 v[6:7], v[6:7], 0, s[6:7]
	v_lshl_add_u64 v[8:9], v[8:9], 0, s[10:11]
	s_add_i32 s25, s18, 13
	s_cmpk_gt_u32 s25, 0x3ff
	s_cbranch_scc1 .Lscan_ldsmall_w
	s_add_i32 s16, s15, 0x2000
	s_mov_b32 m0, s16
	s_mov_b32 exec_hi, 0
	s_add_i32 s15, s15, 0x2800
	global_load_lds_dwordx4 v[2:3], off
	global_load_lds_dwordx4 v[4:5], off offset:512
	global_load_lds_dwordx4 v[6:7], off offset:1024
	s_mov_b32 exec_lo, 0xffff
	s_cmp_eq_u32 s15, 0x25800
	global_load_lds_dwordx4 v[8:9], off offset:1536
	s_mov_b64 exec, -1
	s_cselect_b32 s15, 0, s15
	v_lshl_add_u64 v[2:3], v[2:3], 0, s[6:7]
	v_lshl_add_u64 v[4:5], v[4:5], 0, s[6:7]
	v_lshl_add_u64 v[6:7], v[6:7], 0, s[6:7]
	v_lshl_add_u64 v[8:9], v[8:9], 0, s[10:11]
	s_add_i32 s25, s18, 14
	s_cmpk_gt_u32 s25, 0x3ff
	s_cbranch_scc1 .Lscan_ldsmall_w
	s_add_i32 s16, s15, 0x2000
	s_mov_b32 m0, s16
	s_mov_b32 exec_hi, 0
	s_add_i32 s15, s15, 0x2800
	global_load_lds_dwordx4 v[2:3], off
	global_load_lds_dwordx4 v[4:5], off offset:512
	global_load_lds_dwordx4 v[6:7], off offset:1024
	s_mov_b32 exec_lo, 0xffff
	s_cmp_eq_u32 s15, 0x25800
	global_load_lds_dwordx4 v[8:9], off offset:1536
	s_mov_b64 exec, -1
	s_cselect_b32 s15, 0, s15
	v_lshl_add_u64 v[2:3], v[2:3], 0, s[6:7]
	v_lshl_add_u64 v[4:5], v[4:5], 0, s[6:7]
	v_lshl_add_u64 v[6:7], v[6:7], 0, s[6:7]
	v_lshl_add_u64 v[8:9], v[8:9], 0, s[10:11]
	s_waitcnt vmcnt(24)
	s_branch .Lscan_ldsmall_bar

; #define SP_BAR() asm volatile("s_waitcnt lgkmcnt(0)\n\ts_barrier" ::: "memory")
; __device__ __forceinline__ void p3_rwkv_state(Frame& F, const Args& a) {
;     ...
;     } else {
;         for (int n = 0; n < NC / 2 + 1; ++n) SP_BAR();
;     }
.Lscan_idle:
	s_movk_i32 s1, 0x101

; __device__ __forceinline__ void p3_rwkv_state(Frame& F, const Args& a) {
;     ...
;         for (int n = 0; n < NC; n += 2) { SP_STEP(C, N, n); SP_STEP(N, C, n + 1); }
.Lscan_loop:
	v_add_u32_e32 v80, s10, v77
	v_add_u32_e32 v81, s10, v78
	v_add_u32_e32 v82, s10, v79
	s_add_i32 s10, s10, 0x2800
	s_cmp_eq_u32 s10, 0x25800
	s_cselect_b32 s10, 0, s10
	v_mfma_f32_16x16x32_bf16 v[24:27], v[32:35], v[16:19], v[24:27]
	v_mfma_f32_16x16x32_bf16 v[28:31], v[40:43], v[16:19], v[28:31]
	v_mfma_f32_16x16x32_bf16 v[24:27], v[36:39], v[20:23], v[24:27]
	v_mfma_f32_16x16x32_bf16 v[28:31], v[44:47], v[20:23], v[28:31]
	ds_read_b128 v[32:35], v80
	ds_read_b128 v[36:39], v80 offset:1024
	ds_read_b128 v[40:43], v80 offset:2048
	ds_read_b128 v[44:47], v80 offset:3072
	ds_read2st64_b64 v[96:99], v81 offset0:16 offset1:17
	s_waitcnt lgkmcnt(10)
	v_pk_mul_f32 v[0:1], v[64:65], v[0:1]
	v_pk_mul_f32 v[2:3], v[66:67], v[2:3]
	v_pk_mul_f32 v[4:5], v[68:69], v[4:5]
	v_pk_mul_f32 v[6:7], v[70:71], v[6:7]
	v_pk_mul_f32 v[8:9], v[72:73], v[8:9]
	v_pk_mul_f32 v[10:11], v[74:75], v[10:11]
	v_pk_mul_f32 v[12:13], v[88:89], v[12:13]
	v_pk_mul_f32 v[14:15], v[90:91], v[14:15]
	ds_read_b128 v[64:67], v82 offset:9728
	ds_read_b128 v[68:71], v82 offset:9744
	ds_read_b128 v[72:75], v82 offset:9760
	ds_read_b128 v[88:91], v82 offset:9776
	v_cvt_pk_bf16_f32 v94, v24, v25
	v_cvt_pk_bf16_f32 v95, v26, v27
	s_waitcnt lgkmcnt(9)
	s_nop 1
	v_mfma_f32_16x16x32_bf16 v[0:3], v[48:51], v[92:95], v[0:3]
	v_mfma_f32_16x16x32_bf16 v[4:7], v[52:55], v[92:95], v[4:7]
	v_mfma_f32_16x16x32_bf16 v[8:11], v[56:59], v[92:95], v[8:11]
	v_mfma_f32_16x16x32_bf16 v[12:15], v[60:63], v[92:95], v[12:15]
	v_cvt_pk_bf16_f32 v84, v28, v29
	v_cvt_pk_bf16_f32 v85, v30, v31
	ds_read2st64_b64 v[48:51], v81 offset0:12 offset1:8
	ds_read2st64_b64 v[52:55], v81 offset0:13 offset1:9
	ds_read2st64_b64 v[56:59], v81 offset0:14 offset1:10
	ds_read2st64_b64 v[60:63], v81 offset0:15 offset1:11
	ds_read_b64 v[92:93], v81 offset:9216
	global_store_dwordx2 v78, v[84:85], s[8:9]
	s_add_u32 s8, s8, 0x8000
	s_addc_u32 s9, s9, 0
	s_waitcnt lgkmcnt(9)
	v_lshlrev_b32_e32 v24, 16, v96
	v_and_b32_e32 v25, 0xffff0000, v96
	v_lshlrev_b32_e32 v26, 16, v97
	v_and_b32_e32 v27, 0xffff0000, v97
	v_lshlrev_b32_e32 v28, 16, v98
	v_and_b32_e32 v29, 0xffff0000, v98
	v_lshlrev_b32_e32 v30, 16, v99
	v_and_b32_e32 v31, 0xffff0000, v99
	v_cvt_pk_bf16_f32 v16, v0, v1
	v_cvt_pk_bf16_f32 v17, v2, v3
	v_cvt_pk_bf16_f32 v18, v4, v5
	v_cvt_pk_bf16_f32 v19, v6, v7
	v_cvt_pk_bf16_f32 v20, v8, v9
	v_cvt_pk_bf16_f32 v21, v10, v11
	v_cvt_pk_bf16_f32 v22, v12, v13
	v_cvt_pk_bf16_f32 v23, v14, v15
	v_add_u32_e32 v80, s10, v77
	v_add_u32_e32 v81, s10, v78
	v_add_u32_e32 v82, s10, v79
	s_add_i32 s10, s10, 0x2800
	s_cmp_eq_u32 s10, 0x25800
	s_cselect_b32 s10, 0, s10
	v_mfma_f32_16x16x32_bf16 v[24:27], v[32:35], v[16:19], v[24:27]
	v_mfma_f32_16x16x32_bf16 v[28:31], v[40:43], v[16:19], v[28:31]
	v_mfma_f32_16x16x32_bf16 v[24:27], v[36:39], v[20:23], v[24:27]
	v_mfma_f32_16x16x32_bf16 v[28:31], v[44:47], v[20:23], v[28:31]
	ds_read_b128 v[32:35], v80
	ds_read_b128 v[36:39], v80 offset:1024
	ds_read_b128 v[40:43], v80 offset:2048
	ds_read_b128 v[44:47], v80 offset:3072
	ds_read2st64_b64 v[96:99], v81 offset0:16 offset1:17
	s_waitcnt lgkmcnt(10)
	v_pk_mul_f32 v[0:1], v[64:65], v[0:1]
	v_pk_mul_f32 v[2:3], v[66:67], v[2:3]
	v_pk_mul_f32 v[4:5], v[68:69], v[4:5]
	v_pk_mul_f32 v[6:7], v[70:71], v[6:7]
	v_pk_mul_f32 v[8:9], v[72:73], v[8:9]
	v_pk_mul_f32 v[10:11], v[74:75], v[10:11]
	v_pk_mul_f32 v[12:13], v[88:89], v[12:13]
	v_pk_mul_f32 v[14:15], v[90:91], v[14:15]
	ds_read_b128 v[64:67], v82 offset:9728
	ds_read_b128 v[68:71], v82 offset:9744
	ds_read_b128 v[72:75], v82 offset:9760
	ds_read_b128 v[88:91], v82 offset:9776
	v_cvt_pk_bf16_f32 v94, v24, v25
	v_cvt_pk_bf16_f32 v95, v26, v27
	s_waitcnt lgkmcnt(9)
	s_nop 1
	v_mfma_f32_16x16x32_bf16 v[0:3], v[48:51], v[92:95], v[0:3]
	v_mfma_f32_16x16x32_bf16 v[4:7], v[52:55], v[92:95], v[4:7]
	v_mfma_f32_16x16x32_bf16 v[8:11], v[56:59], v[92:95], v[8:11]
	v_mfma_f32_16x16x32_bf16 v[12:15], v[60:63], v[92:95], v[12:15]
	v_cvt_pk_bf16_f32 v84, v28, v29
	v_cvt_pk_bf16_f32 v85, v30, v31
	ds_read2st64_b64 v[48:51], v81 offset0:12 offset1:8
	ds_read2st64_b64 v[52:55], v81 offset0:13 offset1:9
	ds_read2st64_b64 v[56:59], v81 offset0:14 offset1:10
	ds_read2st64_b64 v[60:63], v81 offset0:15 offset1:11
	ds_read_b64 v[92:93], v81 offset:9216
	global_store_dwordx2 v78, v[84:85], s[8:9]
	s_add_u32 s8, s8, 0x8000
	s_addc_u32 s9, s9, 0
	s_waitcnt lgkmcnt(9)
; __device__ __forceinline__ void p3_rwkv_state(Frame& F, const Args& a) {
;     ...
;         for (int n = 0; n < NC; n += 2) { SP_STEP(C, N, n); SP_STEP(N, C, n + 1); }
	v_lshlrev_b32_e32 v24, 16, v96
	v_and_b32_e32 v25, 0xffff0000, v96
	v_lshlrev_b32_e32 v26, 16, v97
	v_and_b32_e32 v27, 0xffff0000, v97
	v_lshlrev_b32_e32 v28, 16, v98
	v_and_b32_e32 v29, 0xffff0000, v98
	v_lshlrev_b32_e32 v30, 16, v99
	v_and_b32_e32 v31, 0xffff0000, v99
	v_cvt_pk_bf16_f32 v16, v0, v1
	v_cvt_pk_bf16_f32 v17, v2, v3
	v_cvt_pk_bf16_f32 v18, v4, v5
	v_cvt_pk_bf16_f32 v19, v6, v7
	v_cvt_pk_bf16_f32 v20, v8, v9
	v_cvt_pk_bf16_f32 v21, v10, v11
	v_cvt_pk_bf16_f32 v22, v12, v13
	v_cvt_pk_bf16_f32 v23, v14, v15
	v_add_u32_e32 v80, s10, v77
	v_add_u32_e32 v81, s10, v78
	v_add_u32_e32 v82, s10, v79
	s_add_i32 s10, s10, 0x2800
	s_cmp_eq_u32 s10, 0x25800
	s_cselect_b32 s10, 0, s10
	v_mfma_f32_16x16x32_bf16 v[24:27], v[32:35], v[16:19], v[24:27]
	v_mfma_f32_16x16x32_bf16 v[28:31], v[40:43], v[16:19], v[28:31]
	v_mfma_f32_16x16x32_bf16 v[24:27], v[36:39], v[20:23], v[24:27]
	v_mfma_f32_16x16x32_bf16 v[28:31], v[44:47], v[20:23], v[28:31]
	ds_read_b128 v[32:35], v80
	ds_read_b128 v[36:39], v80 offset:1024
	ds_read_b128 v[40:43], v80 offset:2048
	ds_read_b128 v[44:47], v80 offset:3072
	ds_read2st64_b64 v[96:99], v81 offset0:16 offset1:17
	s_waitcnt lgkmcnt(10)
	v_pk_mul_f32 v[0:1], v[64:65], v[0:1]
	v_pk_mul_f32 v[2:3], v[66:67], v[2:3]
	v_pk_mul_f32 v[4:5], v[68:69], v[4:5]
	v_pk_mul_f32 v[6:7], v[70:71], v[6:7]
	v_pk_mul_f32 v[8:9], v[72:73], v[8:9]
	v_pk_mul_f32 v[10:11], v[74:75], v[10:11]
	v_pk_mul_f32 v[12:13], v[88:89], v[12:13]
	v_pk_mul_f32 v[14:15], v[90:91], v[14:15]
	ds_read_b128 v[64:67], v82 offset:9728
	ds_read_b128 v[68:71], v82 offset:9744
	ds_read_b128 v[72:75], v82 offset:9760
	ds_read_b128 v[88:91], v82 offset:9776
	v_cvt_pk_bf16_f32 v94, v24, v25
	v_cvt_pk_bf16_f32 v95, v26, v27
	s_waitcnt lgkmcnt(9)
	s_nop 1
	v_mfma_f32_16x16x32_bf16 v[0:3], v[48:51], v[92:95], v[0:3]
	v_mfma_f32_16x16x32_bf16 v[4:7], v[52:55], v[92:95], v[4:7]
	v_mfma_f32_16x16x32_bf16 v[8:11], v[56:59], v[92:95], v[8:11]
	v_mfma_f32_16x16x32_bf16 v[12:15], v[60:63], v[92:95], v[12:15]
	v_cvt_pk_bf16_f32 v84, v28, v29
	v_cvt_pk_bf16_f32 v85, v30, v31
	ds_read2st64_b64 v[48:51], v81 offset0:12 offset1:8
	ds_read2st64_b64 v[52:55], v81 offset0:13 offset1:9
	ds_read2st64_b64 v[56:59], v81 offset0:14 offset1:10
	ds_read2st64_b64 v[60:63], v81 offset0:15 offset1:11
	ds_read_b64 v[92:93], v81 offset:9216
	global_store_dwordx2 v78, v[84:85], s[8:9]
	s_add_u32 s8, s8, 0x8000
	s_addc_u32 s9, s9, 0
	s_waitcnt lgkmcnt(9)
	v_lshlrev_b32_e32 v24, 16, v96
	v_and_b32_e32 v25, 0xffff0000, v96
	v_lshlrev_b32_e32 v26, 16, v97
	v_and_b32_e32 v27, 0xffff0000, v97
	v_lshlrev_b32_e32 v28, 16, v98
	v_and_b32_e32 v29, 0xffff0000, v98
	v_lshlrev_b32_e32 v30, 16, v99
	v_and_b32_e32 v31, 0xffff0000, v99
	v_cvt_pk_bf16_f32 v16, v0, v1
	v_cvt_pk_bf16_f32 v17, v2, v3
	v_cvt_pk_bf16_f32 v18, v4, v5
	v_cvt_pk_bf16_f32 v19, v6, v7
	v_cvt_pk_bf16_f32 v20, v8, v9
	v_cvt_pk_bf16_f32 v21, v10, v11
	v_cvt_pk_bf16_f32 v22, v12, v13
	v_cvt_pk_bf16_f32 v23, v14, v15
	v_add_u32_e32 v80, s10, v77
	v_add_u32_e32 v81, s10, v78
	v_add_u32_e32 v82, s10, v79
	s_add_i32 s10, s10, 0x2800
	s_cmp_eq_u32 s10, 0x25800
	s_cselect_b32 s10, 0, s10
	v_mfma_f32_16x16x32_bf16 v[24:27], v[32:35], v[16:19], v[24:27]
	v_mfma_f32_16x16x32_bf16 v[28:31], v[40:43], v[16:19], v[28:31]
	v_mfma_f32_16x16x32_bf16 v[24:27], v[36:39], v[20:23], v[24:27]
	v_mfma_f32_16x16x32_bf16 v[28:31], v[44:47], v[20:23], v[28:31]
	ds_read_b128 v[32:35], v80
	ds_read_b128 v[36:39], v80 offset:1024
	ds_read_b128 v[40:43], v80 offset:2048
	ds_read_b128 v[44:47], v80 offset:3072
	ds_read2st64_b64 v[96:99], v81 offset0:16 offset1:17
	s_waitcnt lgkmcnt(10)
	v_pk_mul_f32 v[0:1], v[64:65], v[0:1]
	v_pk_mul_f32 v[2:3], v[66:67], v[2:3]
	v_pk_mul_f32 v[4:5], v[68:69], v[4:5]
	v_pk_mul_f32 v[6:7], v[70:71], v[6:7]
	v_pk_mul_f32 v[8:9], v[72:73], v[8:9]
	v_pk_mul_f32 v[10:11], v[74:75], v[10:11]
	v_pk_mul_f32 v[12:13], v[88:89], v[12:13]
	v_pk_mul_f32 v[14:15], v[90:91], v[14:15]
	ds_read_b128 v[64:67], v82 offset:9728
	ds_read_b128 v[68:71], v82 offset:9744
	ds_read_b128 v[72:75], v82 offset:9760
	ds_read_b128 v[88:91], v82 offset:9776
	v_cvt_pk_bf16_f32 v94, v24, v25
	v_cvt_pk_bf16_f32 v95, v26, v27
	s_waitcnt lgkmcnt(9)
	s_nop 1
	v_mfma_f32_16x16x32_bf16 v[0:3], v[48:51], v[92:95], v[0:3]
	v_mfma_f32_16x16x32_bf16 v[4:7], v[52:55], v[92:95], v[4:7]
	v_mfma_f32_16x16x32_bf16 v[8:11], v[56:59], v[92:95], v[8:11]
	v_mfma_f32_16x16x32_bf16 v[12:15], v[60:63], v[92:95], v[12:15]
	v_cvt_pk_bf16_f32 v84, v28, v29
	v_cvt_pk_bf16_f32 v85, v30, v31
	ds_read2st64_b64 v[48:51], v81 offset0:12 offset1:8
	ds_read2st64_b64 v[52:55], v81 offset0:13 offset1:9
	ds_read2st64_b64 v[56:59], v81 offset0:14 offset1:10
	ds_read2st64_b64 v[60:63], v81 offset0:15 offset1:11
	ds_read_b64 v[92:93], v81 offset:9216
	global_store_dwordx2 v78, v[84:85], s[8:9]
	s_add_u32 s8, s8, 0x8000
	s_addc_u32 s9, s9, 0
	s_waitcnt lgkmcnt(9)
	v_lshlrev_b32_e32 v24, 16, v96
	v_and_b32_e32 v25, 0xffff0000, v96
	v_lshlrev_b32_e32 v26, 16, v97
	v_and_b32_e32 v27, 0xffff0000, v97
	v_lshlrev_b32_e32 v28, 16, v98
	v_and_b32_e32 v29, 0xffff0000, v98
	v_lshlrev_b32_e32 v30, 16, v99
	v_and_b32_e32 v31, 0xffff0000, v99
	v_cvt_pk_bf16_f32 v16, v0, v1
	v_cvt_pk_bf16_f32 v17, v2, v3
	v_cvt_pk_bf16_f32 v18, v4, v5
	v_cvt_pk_bf16_f32 v19, v6, v7
	v_cvt_pk_bf16_f32 v20, v8, v9
	v_cvt_pk_bf16_f32 v21, v10, v11
	v_cvt_pk_bf16_f32 v22, v12, v13
	v_cvt_pk_bf16_f32 v23, v14, v15
	s_barrier
	s_add_i32 s11, s11, 4
	s_cmpk_lt_u32 s11, 0x400
	s_cbranch_scc1 .Lscan_loop
	s_branch .LBB0_456
